# attention row sums as v_pk_add_f32 (q64 loop and the hand-written latent diff softmax+PV block)
# speedup vs baseline: 1.0672x; 1.0028x over previous
; DI f32x16 mfma32(bf8 a, bf8 b, f32x16 c) { return __builtin_amdgcn_mfma_f32_32x32x16_bf16(a, b, c, 0, 0, 0); }
; DI float ex2(float x) { return __builtin_amdgcn_exp2f(x); }
; DI float shx(float v, int lane, int mask) { return __int_as_float(__builtin_amdgcn_ds_bpermute((lane ^ mask) << 2, __float_as_int(v))); }
; DI void attn_item_q64(const AttnArgs& a, char* smem) {
;     ...
;     for (int kb = 0; kb < 2; ++kb) {
; #pragma unroll
;       for (int q2 = 0; q2 < 2; ++q2)
; #pragma unroll
;         for (int i = 0; i < 16; ++i) s[q2][kb][i] = 0.f;
; #pragma unroll
;       for (int ks = 0; ks < 4; ++ks) {
;         const bf8 kf = *(const bf8*)(Ks + kb * 32 * 128 + koff[ks]);
; #pragma unroll
;         for (int q2 = 0; q2 < 2; ++q2) s[q2][kb] = mfma32(kf, qf[q2][ks], s[q2][kb]);
;       }
;     }
;     constexpr float SC = 0.125f * LOG2E;
; #pragma unroll
;     for (int q2 = 0; q2 < 2; ++q2) {
;       float mx = -INFINITY;
; #pragma unroll
;       for (int kb = 0; kb < 2; ++kb)
; #pragma unroll
;         for (int i = 0; i < 16; i += 2) mx = fmaxf(fmaxf(mx, s[q2][kb][i]), s[q2][kb][i + 1]);
;       mx = fmaxf(mx, shx(mx, lane, 32)) * SC;
;       const float mn = fmaxf(m[q2], mx);
;       const bool resc = __builtin_amdgcn_ballot_w64(mn != m[q2]) != 0ull;
;       float ps0 = 0.f, ps1 = 0.f;
; #pragma unroll
;       for (int kb = 0; kb < 2; ++kb)
; #pragma unroll
;         for (int i = 0; i < 16; i += 2) {
;           f32x2n v = {s[q2][kb][i], s[q2][kb][i + 1]};
;           v = v * f32x2n{SC, SC} - f32x2n{mn, mn};
;           const float p0 = ex2(v.x), p1 = ex2(v.y);
;           s[q2][kb][i] = p0; s[q2][kb][i + 1] = p1;
;           ps0 += p0; ps1 += p1;
;         }
;       if (resc) {
;         const float alpha = ex2(m[q2] - mn);
;         m[q2] = mn;
;         lsum[q2] *= alpha;
; #pragma unroll
;         for (int d = 0; d < 2; ++d)
; #pragma unroll
;           for (int i = 0; i < 16; ++i) O[q2][d][i] *= alpha;
;       }
;       lsum[q2] += ps0 + ps1;
.LBB0_422:
	s_add_i32 s13, s13, 1
	s_add_u32 s2, s2, 0x2000
	s_addc_u32 s3, s3, 0
	s_mov_b64 s[14:15], 0x80
	s_cmp_lg_u32 s2, 0x48000
	v_lshl_add_u64 v[168:169], v[168:169], 0, s[14:15]
	s_cbranch_scc0 .Lq64_xadds
	v_pk_add_f32 v[242:243], v[66:67], v[68:69]
	v_pk_add_f32 v[242:243], v[82:83], v[242:243]
	v_pk_add_f32 v[242:243], v[84:85], v[242:243]
	v_add_f32_e32 v244, v0, v98
.LBB0_423:
	s_and_b32 s14, s2, 0x2000
	v_or_b32_e32 v0, s14, v176
	s_waitcnt vmcnt(19)
	ds_read_b128 v[66:69], v0
	v_or_b32_e32 v172, s14, v177
	s_waitcnt vmcnt(17)
	ds_read_b128 v[82:85], v172
	v_or_b32_e32 v196, s14, v178
	v_or_b32_e32 v197, s14, v179
	ds_read_b128 v[192:195], v172 offset:4096
	v_mov_b32_e32 v245, v99
	v_pk_add_f32 v[244:245], v[100:101], v[244:245]
	v_pk_add_f32 v[244:245], v[102:103], v[244:245]
	v_pk_add_f32 v[244:245], v[104:105], v[244:245]
	v_pk_add_f32 v[244:245], v[106:107], v[244:245]
	v_pk_add_f32 v[244:245], v[108:109], v[244:245]
	v_pk_add_f32 v[244:245], v[110:111], v[244:245]
	v_pk_add_f32 v[244:245], v[112:113], v[244:245]
	v_pk_add_f32 v[242:243], v[70:71], v[242:243]
	v_pk_add_f32 v[242:243], v[72:73], v[242:243]
	v_pk_add_f32 v[242:243], v[74:75], v[242:243]
	v_pk_add_f32 v[242:243], v[76:77], v[242:243]
	v_pk_add_f32 v[242:243], v[78:79], v[242:243]
	v_pk_add_f32 v[242:243], v[80:81], v[242:243]
	s_waitcnt vmcnt(7) lgkmcnt(2)
	v_mfma_f32_32x32x16_bf16 v[98:113], v[66:69], v[130:133], 0
	s_waitcnt vmcnt(3)
	v_mfma_f32_32x32x16_bf16 v[66:81], v[66:69], v[146:149], 0
	v_pk_add_f32 v[244:245], v[114:115], v[244:245]
	v_pk_add_f32 v[244:245], v[116:117], v[244:245]
	v_pk_add_f32 v[244:245], v[118:119], v[244:245]
	s_waitcnt lgkmcnt(1)
	v_mfma_f32_32x32x16_bf16 v[98:113], v[82:85], v[134:137], v[98:113]
	v_pk_add_f32 v[244:245], v[120:121], v[244:245]
	v_pk_add_f32 v[244:245], v[122:123], v[244:245]
	v_pk_add_f32 v[244:245], v[124:125], v[244:245]
	s_waitcnt vmcnt(2)
	v_mfma_f32_32x32x16_bf16 v[66:81], v[82:85], v[150:153], v[66:81]
	v_pk_add_f32 v[244:245], v[126:127], v[244:245]
	v_add_f32_e32 v245, v128, v245
	v_pk_add_f32 v[242:243], v[86:87], v[242:243]
	ds_read_b128 v[82:85], v196
	s_waitcnt lgkmcnt(0)
	v_mfma_f32_32x32x16_bf16 v[98:113], v[82:85], v[138:141], v[98:113]
	v_pk_add_f32 v[242:243], v[88:89], v[242:243]
	v_pk_add_f32 v[242:243], v[90:91], v[242:243]
	v_pk_add_f32 v[242:243], v[92:93], v[242:243]
	s_waitcnt vmcnt(1)
	v_mfma_f32_32x32x16_bf16 v[66:81], v[82:85], v[154:157], v[66:81]
	v_pk_add_f32 v[242:243], v[94:95], v[242:243]
	v_pk_add_f32 v[242:243], v[96:97], v[242:243]
	ds_read_b128 v[82:85], v197
	s_waitcnt lgkmcnt(0)
	v_mfma_f32_32x32x16_bf16 v[98:113], v[82:85], v[142:145], v[98:113]
	s_waitcnt vmcnt(0)
	v_mfma_f32_32x32x16_bf16 v[66:81], v[82:85], v[158:161], v[66:81]
	ds_read_b128 v[82:85], v0 offset:4096
	v_add_f32_e32 v242, v242, v243
	v_add_f32_e32 v174, v242, v174
	v_add_f32_e32 v244, v244, v245
	v_add_f32_e32 v189, v244, v189
	s_nop 8
	v_max3_f32 v0, v98, s33, v99
	v_max3_f32 v0, v0, v100, v101
	v_max3_f32 v0, v0, v102, v103
	v_max3_f32 v0, v0, v104, v105
	v_max3_f32 v0, v0, v106, v107
	v_max3_f32 v0, v0, v108, v109
	s_waitcnt lgkmcnt(0)
	v_mfma_f32_32x32x16_bf16 v[114:129], v[82:85], v[130:133], 0
	v_max3_f32 v0, v0, v110, v111
	v_max3_f32 v0, v0, v112, v113
	v_mfma_f32_32x32x16_bf16 v[82:97], v[82:85], v[146:149], 0
	v_mfma_f32_32x32x16_bf16 v[114:129], v[192:195], v[134:137], v[114:129]
	v_mfma_f32_32x32x16_bf16 v[82:97], v[192:195], v[150:153], v[82:97]
	ds_read_b128 v[192:195], v196 offset:4096
	s_waitcnt lgkmcnt(0)
	v_mfma_f32_32x32x16_bf16 v[114:129], v[192:195], v[138:141], v[114:129]
	v_mfma_f32_32x32x16_bf16 v[82:97], v[192:195], v[154:157], v[82:97]
	ds_read_b128 v[192:195], v197 offset:4096
	s_waitcnt lgkmcnt(0)
	v_mfma_f32_32x32x16_bf16 v[114:129], v[192:195], v[142:145], v[114:129]
	v_mfma_f32_32x32x16_bf16 v[82:97], v[192:195], v[158:161], v[82:97]
	s_nop 10
	v_max3_f32 v0, v0, v114, v115
	v_max3_f32 v0, v0, v116, v117
	v_max3_f32 v0, v0, v118, v119
	v_max3_f32 v0, v0, v120, v121
	v_max3_f32 v0, v0, v122, v123
	v_max3_f32 v0, v0, v124, v125
	v_max3_f32 v0, v0, v126, v127
	v_max3_f32 v0, v0, v128, v129
	v_mul_f32_e32 v172, 0x3e38aa3b, v0
	v_sub_f32_e32 v172, v172, v191
	v_cmp_lt_f32_e32 vcc, 8.0, v172
	s_cbranch_vccnz .Llz_2
	v_mov_b32_e32 v0, v191
	s_branch .LBB0_425

; DI unsigned pack2(float a, float b) { f2 v = {a, b}; bf2 r = __builtin_convertvector(v, bf2); return __builtin_bit_cast(unsigned, r); }
; DI f32x16 mfma32(bf8 a, bf8 b, f32x16 c) { return __builtin_amdgcn_mfma_f32_32x32x16_bf16(a, b, c, 0, 0, 0); }
; DI float ex2(float x) { return __builtin_amdgcn_exp2f(x); }
; template <int DV, int MODE>
; DI void attn_item(const AttnArgs& a, char* smem) {
;     ...
; #pragma unroll
;       for (int kb = 0; kb < 2; ++kb)
; #pragma unroll
;         for (int i = 0; i < 16; i += 2) {
;           f32x2n v = {s[kb][i], s[kb][i + 1]};
;           v = v * f32x2n{SC, SC} - f32x2n{mn, mn};
;           const float p0 = ex2(v.x), p1 = ex2(v.y);
;           s[kb][i] = p0; s[kb][i + 1] = p1;
;           ps0 += p0; ps1 += p1;
;         }
;       if (resc) {
;         const float alpha = ex2(m - mn);
;         m = mn;
;         lsum *= alpha;
; #pragma unroll
;         for (int d = 0; d < NDV; ++d)
; #pragma unroll
;           for (int i = 0; i < 16; ++i) O[d][i] *= alpha;
;       }
;       lsum += ps0 + ps1;
; #pragma unroll
;       for (int kb = 0; kb < 2; ++kb)
; #pragma unroll
;         for (int s2 = 0; s2 < 2; ++s2) {
;           u32x4 pk;
;           pk.x = pack2(s[kb][s2 * 8 + 0], s[kb][s2 * 8 + 1]);
;           pk.y = pack2(s[kb][s2 * 8 + 2], s[kb][s2 * 8 + 3]);
;           pk.z = pack2(s[kb][s2 * 8 + 4], s[kb][s2 * 8 + 5]);
;           pk.w = pack2(s[kb][s2 * 8 + 6], s[kb][s2 * 8 + 7]);
;           const bf8 pf = __builtin_bit_cast(bf8, pk);
; #pragma unroll
;           for (int d = 0; d < NDV; ++d) {
;             const u16* vp = Vs + (d * 32 + r) * 72 + kb * 32 + s2 * 16 + 4 * h;
;             u32x4 vv;
;             const u32x2 lo = *(const u32x2*)(vp);
;             const u32x2 hi = *(const u32x2*)(vp + 8);
;             vv.x = lo.x; vv.y = lo.y; vv.z = hi.x; vv.w = hi.y;
;             O[d] = mfma32(__builtin_bit_cast(bf8, vv), pf, O[d]);
;           }
;         }
.LBB0_553:
	s_add_i32 s3, s3, 1
	s_add_i32 s0, s0, 64
	v_add_u32_e32 v237, 0x4800, v154
	v_add_u32_e32 v250, 0x5800, v154
	v_add_u32_e32 v251, 0x6800, v154
	v_add_u32_e32 v160, 0x7800, v154
	ds_read2_b64 v[238:241], v237 offset1:2
	ds_read2_b64 v[242:245], v250 offset0:64 offset1:66
	ds_read2_b64 v[246:249], v251 offset0:128 offset1:130
	ds_read2_b64 v[252:255], v160 offset0:192 offset1:194
	v_mov_b32_e32 v168, 0
	v_mov_b32_e32 v169, 0
	v_pk_fma_f32 v[82:83], v[82:83], s[24:25], v[148:149] op_sel_hi:[1,0,0] neg_lo:[0,0,1] neg_hi:[0,0,1]
	v_pk_fma_f32 v[84:85], v[84:85], s[24:25], v[148:149] op_sel_hi:[1,0,0] neg_lo:[0,0,1] neg_hi:[0,0,1]
	v_pk_fma_f32 v[86:87], v[86:87], s[24:25], v[148:149] op_sel_hi:[1,0,0] neg_lo:[0,0,1] neg_hi:[0,0,1]
	v_pk_fma_f32 v[88:89], v[88:89], s[24:25], v[148:149] op_sel_hi:[1,0,0] neg_lo:[0,0,1] neg_hi:[0,0,1]
	v_exp_f32_e32 v82, v82
	v_exp_f32_e32 v83, v83
	v_exp_f32_e32 v84, v84
	v_exp_f32_e32 v85, v85
	v_exp_f32_e32 v86, v86
	v_exp_f32_e32 v87, v87
	v_exp_f32_e32 v88, v88
	v_exp_f32_e32 v89, v89
	v_cvt_pk_bf16_f32 v156, v82, v83
	v_cvt_pk_bf16_f32 v157, v84, v85
	v_cvt_pk_bf16_f32 v158, v86, v87
	v_cvt_pk_bf16_f32 v159, v88, v89
	v_pk_add_f32 v[168:169], v[82:83], v[168:169]
	v_pk_add_f32 v[168:169], v[84:85], v[168:169]
	v_pk_add_f32 v[168:169], v[86:87], v[168:169]
	v_pk_add_f32 v[168:169], v[88:89], v[168:169]
	s_waitcnt lgkmcnt(3)
	v_mfma_f32_32x32x16_bf16 v[50:65], v[238:241], v[156:159], v[50:65]
	ds_read2_b64 v[238:241], v237 offset0:4 offset1:6
	v_pk_fma_f32 v[90:91], v[90:91], s[24:25], v[148:149] op_sel_hi:[1,0,0] neg_lo:[0,0,1] neg_hi:[0,0,1]
	v_pk_fma_f32 v[92:93], v[92:93], s[24:25], v[148:149] op_sel_hi:[1,0,0] neg_lo:[0,0,1] neg_hi:[0,0,1]
	v_pk_fma_f32 v[94:95], v[94:95], s[24:25], v[148:149] op_sel_hi:[1,0,0] neg_lo:[0,0,1] neg_hi:[0,0,1]
	v_pk_fma_f32 v[96:97], v[96:97], s[24:25], v[148:149] op_sel_hi:[1,0,0] neg_lo:[0,0,1] neg_hi:[0,0,1]
	v_exp_f32_e32 v90, v90
	v_exp_f32_e32 v91, v91
	s_waitcnt lgkmcnt(3)
	v_mfma_f32_32x32x16_bf16 v[34:49], v[242:245], v[156:159], v[34:49]
	ds_read2_b64 v[242:245], v250 offset0:68 offset1:70
	v_exp_f32_e32 v92, v92
	v_exp_f32_e32 v93, v93
	v_exp_f32_e32 v94, v94
	v_exp_f32_e32 v95, v95
	v_exp_f32_e32 v96, v96
	v_exp_f32_e32 v97, v97
	s_waitcnt lgkmcnt(3)
	v_mfma_f32_32x32x16_bf16 v[18:33], v[246:249], v[156:159], v[18:33]
	ds_read2_b64 v[246:249], v251 offset0:132 offset1:134
	v_cvt_pk_bf16_f32 v164, v90, v91
	v_cvt_pk_bf16_f32 v165, v92, v93
	v_cvt_pk_bf16_f32 v166, v94, v95
	v_cvt_pk_bf16_f32 v167, v96, v97
	s_waitcnt lgkmcnt(3)
	v_mfma_f32_32x32x16_bf16 v[2:17], v[252:255], v[156:159], v[2:17]
	ds_read2_b64 v[252:255], v160 offset0:196 offset1:198
	v_pk_add_f32 v[168:169], v[90:91], v[168:169]
	v_pk_add_f32 v[168:169], v[92:93], v[168:169]
	v_pk_add_f32 v[168:169], v[94:95], v[168:169]
	v_pk_add_f32 v[168:169], v[96:97], v[168:169]
	s_waitcnt lgkmcnt(3)
	v_mfma_f32_32x32x16_bf16 v[50:65], v[238:241], v[164:167], v[50:65]
	ds_read2_b64 v[238:241], v237 offset0:8 offset1:10
	v_pk_fma_f32 v[66:67], v[66:67], s[24:25], v[148:149] op_sel_hi:[1,0,0] neg_lo:[0,0,1] neg_hi:[0,0,1]
	v_pk_fma_f32 v[68:69], v[68:69], s[24:25], v[148:149] op_sel_hi:[1,0,0] neg_lo:[0,0,1] neg_hi:[0,0,1]
	v_pk_fma_f32 v[70:71], v[70:71], s[24:25], v[148:149] op_sel_hi:[1,0,0] neg_lo:[0,0,1] neg_hi:[0,0,1]
	v_pk_fma_f32 v[72:73], v[72:73], s[24:25], v[148:149] op_sel_hi:[1,0,0] neg_lo:[0,0,1] neg_hi:[0,0,1]
	v_exp_f32_e32 v66, v66
	v_exp_f32_e32 v67, v67
	s_waitcnt lgkmcnt(3)
	v_mfma_f32_32x32x16_bf16 v[34:49], v[242:245], v[164:167], v[34:49]
	ds_read2_b64 v[242:245], v250 offset0:72 offset1:74
	v_exp_f32_e32 v68, v68
	v_exp_f32_e32 v69, v69
	v_exp_f32_e32 v70, v70
	v_exp_f32_e32 v71, v71
	v_exp_f32_e32 v72, v72
	v_exp_f32_e32 v73, v73
	s_waitcnt lgkmcnt(3)
	v_mfma_f32_32x32x16_bf16 v[18:33], v[246:249], v[164:167], v[18:33]
	ds_read2_b64 v[246:249], v251 offset0:136 offset1:138
	v_cvt_pk_bf16_f32 v156, v66, v67
	v_cvt_pk_bf16_f32 v157, v68, v69
	v_cvt_pk_bf16_f32 v158, v70, v71
	v_cvt_pk_bf16_f32 v159, v72, v73
	s_waitcnt lgkmcnt(3)
	v_mfma_f32_32x32x16_bf16 v[2:17], v[252:255], v[164:167], v[2:17]
	ds_read2_b64 v[252:255], v160 offset0:200 offset1:202
	v_pk_add_f32 v[168:169], v[66:67], v[168:169]
	v_pk_add_f32 v[168:169], v[68:69], v[168:169]
	v_pk_add_f32 v[168:169], v[70:71], v[168:169]
	v_pk_add_f32 v[168:169], v[72:73], v[168:169]
	s_waitcnt lgkmcnt(3)
	v_mfma_f32_32x32x16_bf16 v[50:65], v[238:241], v[156:159], v[50:65]
	ds_read2_b64 v[238:241], v237 offset0:12 offset1:14
	v_pk_fma_f32 v[74:75], v[74:75], s[24:25], v[148:149] op_sel_hi:[1,0,0] neg_lo:[0,0,1] neg_hi:[0,0,1]
	v_pk_fma_f32 v[76:77], v[76:77], s[24:25], v[148:149] op_sel_hi:[1,0,0] neg_lo:[0,0,1] neg_hi:[0,0,1]
	v_pk_fma_f32 v[78:79], v[78:79], s[24:25], v[148:149] op_sel_hi:[1,0,0] neg_lo:[0,0,1] neg_hi:[0,0,1]
	v_pk_fma_f32 v[80:81], v[80:81], s[24:25], v[148:149] op_sel_hi:[1,0,0] neg_lo:[0,0,1] neg_hi:[0,0,1]
	v_exp_f32_e32 v74, v74
	v_exp_f32_e32 v75, v75
	s_waitcnt lgkmcnt(3)
	v_mfma_f32_32x32x16_bf16 v[34:49], v[242:245], v[156:159], v[34:49]
	ds_read2_b64 v[242:245], v250 offset0:76 offset1:78
	v_exp_f32_e32 v76, v76
	v_exp_f32_e32 v77, v77
	v_exp_f32_e32 v78, v78
	v_exp_f32_e32 v79, v79
	v_exp_f32_e32 v80, v80
	v_exp_f32_e32 v81, v81
	s_waitcnt lgkmcnt(3)
	v_mfma_f32_32x32x16_bf16 v[18:33], v[246:249], v[156:159], v[18:33]
	ds_read2_b64 v[246:249], v251 offset0:140 offset1:142
	v_cvt_pk_bf16_f32 v164, v74, v75
	v_cvt_pk_bf16_f32 v165, v76, v77
	v_cvt_pk_bf16_f32 v166, v78, v79
	v_cvt_pk_bf16_f32 v167, v80, v81
	s_waitcnt lgkmcnt(3)
	v_mfma_f32_32x32x16_bf16 v[2:17], v[252:255], v[156:159], v[2:17]
	ds_read2_b64 v[252:255], v160 offset0:204 offset1:206
	v_pk_add_f32 v[168:169], v[74:75], v[168:169]
	v_pk_add_f32 v[168:169], v[76:77], v[168:169]
	v_pk_add_f32 v[168:169], v[78:79], v[168:169]
	v_pk_add_f32 v[168:169], v[80:81], v[168:169]
	s_waitcnt lgkmcnt(3)
	v_mfma_f32_32x32x16_bf16 v[50:65], v[238:241], v[164:167], v[50:65]
	s_waitcnt lgkmcnt(2)
	v_mfma_f32_32x32x16_bf16 v[34:49], v[242:245], v[164:167], v[34:49]
	s_waitcnt lgkmcnt(1)
	v_mfma_f32_32x32x16_bf16 v[18:33], v[246:249], v[164:167], v[18:33]
	s_waitcnt lgkmcnt(0)
	v_mfma_f32_32x32x16_bf16 v[2:17], v[252:255], v[164:167], v[2:17]
	v_add_f32_e32 v168, v168, v169
	v_add_f32_e32 v152, v168, v152
	s_cmp_eq_u32 s3, 36
	s_cbranch_scc1 .LBB0_558
